# v16 with the nt (streaming) cache hint on the residual epilogue's x loads and stores
# speedup vs baseline: 1.0046x; 1.0046x over previous
.LBB0_293:
	s_ashr_i32 s3, s65, 31
	s_sub_i32 s4, s65, 64
	s_lshr_b32 s24, s65, 4
	s_cmp_gt_i32 s65, 63
	s_cselect_b32 s5, 0, s3
	s_cselect_b32 s4, s4, s65
	s_mulk_i32 s24, 0x4800
	s_waitcnt lgkmcnt(0)
	s_cselect_b32 s3, s15, s91
	s_cselect_b32 s28, s14, s90
	s_cselect_b32 s35, s14, s72
	s_cselect_b32 s42, s15, s73
	s_cselect_b32 s34, 0x12000, s24
	s_lshl_b64 s[4:5], s[4:5], 20
	s_add_u32 s28, s28, s4
	s_addc_u32 s29, s3, s5
	s_add_u32 s4, s35, s4
	s_addc_u32 s5, s42, s5
	s_ashr_i32 s35, s34, 31
	s_lshl_b32 s3, s85, 8
	s_or_b32 s3, s3, s1
	s_lshl_b64 s[34:35], s[34:35], 2
	s_add_u32 s34, s58, s34
	v_lshl_add_u32 v154, v67, 2, s3
	s_addc_u32 s35, s92, s35
	v_ashrrev_i32_e32 v155, 31, v154
	v_lshl_add_u64 v[156:157], v[154:155], 2, s[34:35]
	global_load_dwordx4 v[132:135], v[156:157], off
	global_load_dwordx4 v[136:139], v[156:157], off offset:64
	global_load_dwordx4 v[140:143], v[156:157], off offset:512
	global_load_dwordx4 v[168:171], v[156:157], off offset:576
	v_add_u32_e32 v163, s0, v164
	v_lshlrev_b32_e32 v163, 12, v163
	v_lshl_add_u32 v162, v154, 2, v163
	s_mov_b32 s3, 0xffff8040
	s_mov_b32 s24, 0x8000
	v_mov_b32_e32 v167, v162
	v_cmp_lt_u32_e32 vcc, 7, v164
	v_mov_b32_e32 v243, s3
	v_cndmask_b32_e32 v243, 0, v243, vcc
	v_mov_b32_e32 v163, s24
	v_cndmask_b32_e64 v163, v163, 64, vcc
	v_add_u32_e32 v163, v162, v163
	v_add_u32_e32 v162, v162, v243
	s_andn2_b64 vcc, exec, s[30:31]
	s_cbranch_vccz .Lepi_r_split
	global_load_dwordx4 v[150:153], v162, s[28:29] nt
	global_load_dwordx4 v[154:157], v163, s[28:29] nt
	global_load_dwordx4 v[158:161], v162, s[28:29] offset:512 nt
	global_load_dwordx4 v[244:247], v163, s[28:29] offset:512 nt
	s_add_u32 s28, s28, 0x10000
	s_addc_u32 s29, s29, 0
	global_load_dwordx4 v[248:251], v162, s[28:29] nt
	global_load_dwordx4 v[252:255], v163, s[28:29] nt
	global_load_dwordx4 v[172:175], v162, s[28:29] offset:512 nt
	global_load_dwordx4 v[176:179], v163, s[28:29] offset:512 nt
	s_add_u32 s28, s28, 0x10000
	s_addc_u32 s29, s29, 0
	global_load_dwordx4 v[190:193], v162, s[28:29] nt
	global_load_dwordx4 v[194:197], v163, s[28:29] nt
	global_load_dwordx4 v[198:201], v162, s[28:29] offset:512 nt
	global_load_dwordx4 v[202:205], v163, s[28:29] offset:512 nt
	s_add_u32 s28, s28, 0x10000
	s_addc_u32 s29, s29, 0
	global_load_dwordx4 v[206:209], v162, s[28:29] nt
	global_load_dwordx4 v[210:213], v163, s[28:29] nt
	global_load_dwordx4 v[214:217], v162, s[28:29] offset:512 nt
	global_load_dwordx4 v[228:231], v163, s[28:29] offset:512 nt
	s_waitcnt vmcnt(16)
	v_mul_f32_e32 v132, s88, v132
	v_mul_f32_e32 v133, s88, v133
	v_mul_f32_e32 v134, s88, v134
	v_mul_f32_e32 v135, s88, v135
	v_mul_f32_e32 v136, s88, v136
	v_mul_f32_e32 v137, s88, v137
	v_mul_f32_e32 v138, s88, v138
	v_mul_f32_e32 v139, s88, v139
	v_mul_f32_e32 v140, s88, v140
	v_mul_f32_e32 v141, s88, v141
	v_mul_f32_e32 v142, s88, v142
	v_mul_f32_e32 v143, s88, v143
	v_mul_f32_e32 v168, s88, v168
	v_mul_f32_e32 v169, s88, v169
	v_mul_f32_e32 v170, s88, v170
	v_mul_f32_e32 v171, s88, v171
	v_cmp_gt_u32_e32 vcc, 8, v164
	v_cndmask_b32_e32 v132, v136, v132, vcc
	v_cndmask_b32_e32 v133, v137, v133, vcc
	v_cndmask_b32_e32 v134, v138, v134, vcc
	v_cndmask_b32_e32 v135, v139, v135, vcc
	v_cndmask_b32_e32 v140, v168, v140, vcc
	v_cndmask_b32_e32 v141, v169, v141, vcc
	v_cndmask_b32_e32 v142, v170, v142, vcc
	v_cndmask_b32_e32 v143, v171, v143, vcc
	v_cndmask_b32_dpp v232, v124, v128, vcc row_ror:8 row_mask:0xf bank_mask:0xf
	v_cndmask_b32_dpp v233, v125, v129, vcc row_ror:8 row_mask:0xf bank_mask:0xf
	v_cndmask_b32_dpp v234, v126, v130, vcc row_ror:8 row_mask:0xf bank_mask:0xf
	v_cndmask_b32_dpp v235, v127, v131, vcc row_ror:8 row_mask:0xf bank_mask:0xf
	s_not_b64 vcc, vcc
	v_cndmask_b32_dpp v124, v128, v124, vcc row_ror:8 row_mask:0xf bank_mask:0xf
	v_cndmask_b32_dpp v125, v129, v125, vcc row_ror:8 row_mask:0xf bank_mask:0xf
	v_cndmask_b32_dpp v126, v130, v126, vcc row_ror:8 row_mask:0xf bank_mask:0xf
	v_cndmask_b32_dpp v127, v131, v127, vcc row_ror:8 row_mask:0xf bank_mask:0xf
	s_not_b64 vcc, vcc
	s_waitcnt vmcnt(14)
	v_pk_fma_f32 v[128:129], v[232:233], v[132:133], v[150:151]
	v_pk_fma_f32 v[130:131], v[234:235], v[134:135], v[152:153]
	v_pk_fma_f32 v[124:125], v[124:125], v[132:133], v[154:155]
	v_pk_fma_f32 v[126:127], v[126:127], v[134:135], v[156:157]
	s_add_u32 s28, s28, 0x50000
	s_addc_u32 s29, s29, 0
	global_load_dwordx4 v[150:153], v162, s[28:29] nt
	global_load_dwordx4 v[154:157], v163, s[28:29] nt
	v_cndmask_b32_dpp v232, v116, v120, vcc row_ror:8 row_mask:0xf bank_mask:0xf
	v_cndmask_b32_dpp v233, v117, v121, vcc row_ror:8 row_mask:0xf bank_mask:0xf
	v_cndmask_b32_dpp v234, v118, v122, vcc row_ror:8 row_mask:0xf bank_mask:0xf
	v_cndmask_b32_dpp v235, v119, v123, vcc row_ror:8 row_mask:0xf bank_mask:0xf
	s_not_b64 vcc, vcc
	v_cndmask_b32_dpp v116, v120, v116, vcc row_ror:8 row_mask:0xf bank_mask:0xf
	v_cndmask_b32_dpp v117, v121, v117, vcc row_ror:8 row_mask:0xf bank_mask:0xf
	v_cndmask_b32_dpp v118, v122, v118, vcc row_ror:8 row_mask:0xf bank_mask:0xf
	v_cndmask_b32_dpp v119, v123, v119, vcc row_ror:8 row_mask:0xf bank_mask:0xf
	s_not_b64 vcc, vcc
	s_waitcnt vmcnt(14)
	v_pk_fma_f32 v[120:121], v[232:233], v[140:141], v[158:159]
	v_pk_fma_f32 v[122:123], v[234:235], v[142:143], v[160:161]
	v_pk_fma_f32 v[116:117], v[116:117], v[140:141], v[244:245]
	v_pk_fma_f32 v[118:119], v[118:119], v[142:143], v[246:247]
	global_load_dwordx4 v[158:161], v162, s[28:29] offset:512 nt
	global_load_dwordx4 v[244:247], v163, s[28:29] offset:512 nt
	v_cndmask_b32_dpp v232, v108, v112, vcc row_ror:8 row_mask:0xf bank_mask:0xf
	v_cndmask_b32_dpp v233, v109, v113, vcc row_ror:8 row_mask:0xf bank_mask:0xf
	v_cndmask_b32_dpp v234, v110, v114, vcc row_ror:8 row_mask:0xf bank_mask:0xf
	v_cndmask_b32_dpp v235, v111, v115, vcc row_ror:8 row_mask:0xf bank_mask:0xf
	s_not_b64 vcc, vcc
	v_cndmask_b32_dpp v108, v112, v108, vcc row_ror:8 row_mask:0xf bank_mask:0xf
	v_cndmask_b32_dpp v109, v113, v109, vcc row_ror:8 row_mask:0xf bank_mask:0xf
	v_cndmask_b32_dpp v110, v114, v110, vcc row_ror:8 row_mask:0xf bank_mask:0xf
	v_cndmask_b32_dpp v111, v115, v111, vcc row_ror:8 row_mask:0xf bank_mask:0xf
	s_not_b64 vcc, vcc
	s_waitcnt vmcnt(14)
	v_pk_fma_f32 v[112:113], v[232:233], v[132:133], v[248:249]
	v_pk_fma_f32 v[114:115], v[234:235], v[134:135], v[250:251]
	v_pk_fma_f32 v[108:109], v[108:109], v[132:133], v[252:253]
	v_pk_fma_f32 v[110:111], v[110:111], v[134:135], v[254:255]
	s_add_u32 s28, s28, 0x10000
	s_addc_u32 s29, s29, 0
	global_load_dwordx4 v[248:251], v162, s[28:29] nt
	global_load_dwordx4 v[252:255], v163, s[28:29] nt
	v_cndmask_b32_dpp v232, v100, v104, vcc row_ror:8 row_mask:0xf bank_mask:0xf
	v_cndmask_b32_dpp v233, v101, v105, vcc row_ror:8 row_mask:0xf bank_mask:0xf
	v_cndmask_b32_dpp v234, v102, v106, vcc row_ror:8 row_mask:0xf bank_mask:0xf
	v_cndmask_b32_dpp v235, v103, v107, vcc row_ror:8 row_mask:0xf bank_mask:0xf
	s_not_b64 vcc, vcc
	v_cndmask_b32_dpp v100, v104, v100, vcc row_ror:8 row_mask:0xf bank_mask:0xf
	v_cndmask_b32_dpp v101, v105, v101, vcc row_ror:8 row_mask:0xf bank_mask:0xf
	v_cndmask_b32_dpp v102, v106, v102, vcc row_ror:8 row_mask:0xf bank_mask:0xf
	v_cndmask_b32_dpp v103, v107, v103, vcc row_ror:8 row_mask:0xf bank_mask:0xf
	s_not_b64 vcc, vcc
	s_waitcnt vmcnt(14)
	v_pk_fma_f32 v[104:105], v[232:233], v[140:141], v[172:173]
	v_pk_fma_f32 v[106:107], v[234:235], v[142:143], v[174:175]
	v_pk_fma_f32 v[100:101], v[100:101], v[140:141], v[176:177]
	v_pk_fma_f32 v[102:103], v[102:103], v[142:143], v[178:179]
	global_load_dwordx4 v[172:175], v162, s[28:29] offset:512 nt
	global_load_dwordx4 v[176:179], v163, s[28:29] offset:512 nt
	v_cndmask_b32_dpp v232, v92, v96, vcc row_ror:8 row_mask:0xf bank_mask:0xf
	v_cndmask_b32_dpp v233, v93, v97, vcc row_ror:8 row_mask:0xf bank_mask:0xf
	v_cndmask_b32_dpp v234, v94, v98, vcc row_ror:8 row_mask:0xf bank_mask:0xf
	v_cndmask_b32_dpp v235, v95, v99, vcc row_ror:8 row_mask:0xf bank_mask:0xf
	s_not_b64 vcc, vcc
	v_cndmask_b32_dpp v92, v96, v92, vcc row_ror:8 row_mask:0xf bank_mask:0xf
	v_cndmask_b32_dpp v93, v97, v93, vcc row_ror:8 row_mask:0xf bank_mask:0xf
	v_cndmask_b32_dpp v94, v98, v94, vcc row_ror:8 row_mask:0xf bank_mask:0xf
	v_cndmask_b32_dpp v95, v99, v95, vcc row_ror:8 row_mask:0xf bank_mask:0xf
	s_not_b64 vcc, vcc
	s_waitcnt vmcnt(14)
	v_pk_fma_f32 v[96:97], v[232:233], v[132:133], v[190:191]
	v_pk_fma_f32 v[98:99], v[234:235], v[134:135], v[192:193]
	v_pk_fma_f32 v[92:93], v[92:93], v[132:133], v[194:195]
	v_pk_fma_f32 v[94:95], v[94:95], v[134:135], v[196:197]
	s_add_u32 s28, s28, 0x10000
	s_addc_u32 s29, s29, 0
	global_load_dwordx4 v[190:193], v162, s[28:29] nt
	global_load_dwordx4 v[194:197], v163, s[28:29] nt
	v_cndmask_b32_dpp v232, v84, v88, vcc row_ror:8 row_mask:0xf bank_mask:0xf
	v_cndmask_b32_dpp v233, v85, v89, vcc row_ror:8 row_mask:0xf bank_mask:0xf
	v_cndmask_b32_dpp v234, v86, v90, vcc row_ror:8 row_mask:0xf bank_mask:0xf
	v_cndmask_b32_dpp v235, v87, v91, vcc row_ror:8 row_mask:0xf bank_mask:0xf
	s_not_b64 vcc, vcc
	v_cndmask_b32_dpp v84, v88, v84, vcc row_ror:8 row_mask:0xf bank_mask:0xf
	v_cndmask_b32_dpp v85, v89, v85, vcc row_ror:8 row_mask:0xf bank_mask:0xf
	v_cndmask_b32_dpp v86, v90, v86, vcc row_ror:8 row_mask:0xf bank_mask:0xf
	v_cndmask_b32_dpp v87, v91, v87, vcc row_ror:8 row_mask:0xf bank_mask:0xf
	s_not_b64 vcc, vcc
	s_waitcnt vmcnt(14)
	v_pk_fma_f32 v[88:89], v[232:233], v[140:141], v[198:199]
	v_pk_fma_f32 v[90:91], v[234:235], v[142:143], v[200:201]
	v_pk_fma_f32 v[84:85], v[84:85], v[140:141], v[202:203]
	v_pk_fma_f32 v[86:87], v[86:87], v[142:143], v[204:205]
	global_load_dwordx4 v[198:201], v162, s[28:29] offset:512 nt
	global_load_dwordx4 v[202:205], v163, s[28:29] offset:512 nt
	v_cndmask_b32_dpp v232, v76, v80, vcc row_ror:8 row_mask:0xf bank_mask:0xf
	v_cndmask_b32_dpp v233, v77, v81, vcc row_ror:8 row_mask:0xf bank_mask:0xf
	v_cndmask_b32_dpp v234, v78, v82, vcc row_ror:8 row_mask:0xf bank_mask:0xf
	v_cndmask_b32_dpp v235, v79, v83, vcc row_ror:8 row_mask:0xf bank_mask:0xf
	s_not_b64 vcc, vcc
	v_cndmask_b32_dpp v76, v80, v76, vcc row_ror:8 row_mask:0xf bank_mask:0xf
	v_cndmask_b32_dpp v77, v81, v77, vcc row_ror:8 row_mask:0xf bank_mask:0xf
	v_cndmask_b32_dpp v78, v82, v78, vcc row_ror:8 row_mask:0xf bank_mask:0xf
	v_cndmask_b32_dpp v79, v83, v79, vcc row_ror:8 row_mask:0xf bank_mask:0xf
	s_not_b64 vcc, vcc
	s_waitcnt vmcnt(14)
	v_pk_fma_f32 v[80:81], v[232:233], v[132:133], v[206:207]
	v_pk_fma_f32 v[82:83], v[234:235], v[134:135], v[208:209]
	v_pk_fma_f32 v[76:77], v[76:77], v[132:133], v[210:211]
	v_pk_fma_f32 v[78:79], v[78:79], v[134:135], v[212:213]
	s_add_u32 s28, s28, 0x10000
	s_addc_u32 s29, s29, 0
	global_load_dwordx4 v[206:209], v162, s[28:29] nt
	global_load_dwordx4 v[210:213], v163, s[28:29] nt
	v_cndmask_b32_dpp v232, v68, v72, vcc row_ror:8 row_mask:0xf bank_mask:0xf
	v_cndmask_b32_dpp v233, v69, v73, vcc row_ror:8 row_mask:0xf bank_mask:0xf
	v_cndmask_b32_dpp v234, v70, v74, vcc row_ror:8 row_mask:0xf bank_mask:0xf
	v_cndmask_b32_dpp v235, v71, v75, vcc row_ror:8 row_mask:0xf bank_mask:0xf
	s_not_b64 vcc, vcc
	v_cndmask_b32_dpp v68, v72, v68, vcc row_ror:8 row_mask:0xf bank_mask:0xf
	v_cndmask_b32_dpp v69, v73, v69, vcc row_ror:8 row_mask:0xf bank_mask:0xf
	v_cndmask_b32_dpp v70, v74, v70, vcc row_ror:8 row_mask:0xf bank_mask:0xf
	v_cndmask_b32_dpp v71, v75, v71, vcc row_ror:8 row_mask:0xf bank_mask:0xf
	s_not_b64 vcc, vcc
	s_waitcnt vmcnt(14)
	v_pk_fma_f32 v[72:73], v[232:233], v[140:141], v[214:215]
	v_pk_fma_f32 v[74:75], v[234:235], v[142:143], v[216:217]
	v_pk_fma_f32 v[68:69], v[68:69], v[140:141], v[228:229]
	v_pk_fma_f32 v[70:71], v[70:71], v[142:143], v[230:231]
	global_load_dwordx4 v[214:217], v162, s[28:29] offset:512 nt
	global_load_dwordx4 v[228:231], v163, s[28:29] offset:512 nt
	v_cndmask_b32_dpp v232, v58, v62, vcc row_ror:8 row_mask:0xf bank_mask:0xf
	v_cndmask_b32_dpp v233, v59, v63, vcc row_ror:8 row_mask:0xf bank_mask:0xf
	v_cndmask_b32_dpp v234, v60, v64, vcc row_ror:8 row_mask:0xf bank_mask:0xf
	v_cndmask_b32_dpp v235, v61, v65, vcc row_ror:8 row_mask:0xf bank_mask:0xf
	s_not_b64 vcc, vcc
	v_cndmask_b32_dpp v58, v62, v58, vcc row_ror:8 row_mask:0xf bank_mask:0xf
	v_cndmask_b32_dpp v59, v63, v59, vcc row_ror:8 row_mask:0xf bank_mask:0xf
	v_cndmask_b32_dpp v60, v64, v60, vcc row_ror:8 row_mask:0xf bank_mask:0xf
	v_cndmask_b32_dpp v61, v65, v61, vcc row_ror:8 row_mask:0xf bank_mask:0xf
	s_not_b64 vcc, vcc
	s_waitcnt vmcnt(14)
	v_pk_fma_f32 v[62:63], v[232:233], v[132:133], v[150:151]
	v_pk_fma_f32 v[64:65], v[234:235], v[134:135], v[152:153]
	v_pk_fma_f32 v[58:59], v[58:59], v[132:133], v[154:155]
	v_pk_fma_f32 v[60:61], v[60:61], v[134:135], v[156:157]
	v_cndmask_b32_dpp v232, v50, v54, vcc row_ror:8 row_mask:0xf bank_mask:0xf
	v_cndmask_b32_dpp v233, v51, v55, vcc row_ror:8 row_mask:0xf bank_mask:0xf
	v_cndmask_b32_dpp v234, v52, v56, vcc row_ror:8 row_mask:0xf bank_mask:0xf
	v_cndmask_b32_dpp v235, v53, v57, vcc row_ror:8 row_mask:0xf bank_mask:0xf
	s_not_b64 vcc, vcc
	v_cndmask_b32_dpp v50, v54, v50, vcc row_ror:8 row_mask:0xf bank_mask:0xf
	v_cndmask_b32_dpp v51, v55, v51, vcc row_ror:8 row_mask:0xf bank_mask:0xf
	v_cndmask_b32_dpp v52, v56, v52, vcc row_ror:8 row_mask:0xf bank_mask:0xf
	v_cndmask_b32_dpp v53, v57, v53, vcc row_ror:8 row_mask:0xf bank_mask:0xf
	s_not_b64 vcc, vcc
	s_waitcnt vmcnt(12)
	v_pk_fma_f32 v[54:55], v[232:233], v[140:141], v[158:159]
	v_pk_fma_f32 v[56:57], v[234:235], v[142:143], v[160:161]
	v_pk_fma_f32 v[50:51], v[50:51], v[140:141], v[244:245]
	v_pk_fma_f32 v[52:53], v[52:53], v[142:143], v[246:247]
	v_cndmask_b32_dpp v232, v42, v46, vcc row_ror:8 row_mask:0xf bank_mask:0xf
	v_cndmask_b32_dpp v233, v43, v47, vcc row_ror:8 row_mask:0xf bank_mask:0xf
	v_cndmask_b32_dpp v234, v44, v48, vcc row_ror:8 row_mask:0xf bank_mask:0xf
	v_cndmask_b32_dpp v235, v45, v49, vcc row_ror:8 row_mask:0xf bank_mask:0xf
	s_not_b64 vcc, vcc
	v_cndmask_b32_dpp v42, v46, v42, vcc row_ror:8 row_mask:0xf bank_mask:0xf
	v_cndmask_b32_dpp v43, v47, v43, vcc row_ror:8 row_mask:0xf bank_mask:0xf
	v_cndmask_b32_dpp v44, v48, v44, vcc row_ror:8 row_mask:0xf bank_mask:0xf
	v_cndmask_b32_dpp v45, v49, v45, vcc row_ror:8 row_mask:0xf bank_mask:0xf
	s_not_b64 vcc, vcc
	s_waitcnt vmcnt(10)
	v_pk_fma_f32 v[46:47], v[232:233], v[132:133], v[248:249]
	v_pk_fma_f32 v[48:49], v[234:235], v[134:135], v[250:251]
	v_pk_fma_f32 v[42:43], v[42:43], v[132:133], v[252:253]
	v_pk_fma_f32 v[44:45], v[44:45], v[134:135], v[254:255]
	v_cndmask_b32_dpp v232, v34, v38, vcc row_ror:8 row_mask:0xf bank_mask:0xf
	v_cndmask_b32_dpp v233, v35, v39, vcc row_ror:8 row_mask:0xf bank_mask:0xf
	v_cndmask_b32_dpp v234, v36, v40, vcc row_ror:8 row_mask:0xf bank_mask:0xf
	v_cndmask_b32_dpp v235, v37, v41, vcc row_ror:8 row_mask:0xf bank_mask:0xf
	s_not_b64 vcc, vcc
	v_cndmask_b32_dpp v34, v38, v34, vcc row_ror:8 row_mask:0xf bank_mask:0xf
	v_cndmask_b32_dpp v35, v39, v35, vcc row_ror:8 row_mask:0xf bank_mask:0xf
	v_cndmask_b32_dpp v36, v40, v36, vcc row_ror:8 row_mask:0xf bank_mask:0xf
	v_cndmask_b32_dpp v37, v41, v37, vcc row_ror:8 row_mask:0xf bank_mask:0xf
	s_not_b64 vcc, vcc
	s_waitcnt vmcnt(8)
	v_pk_fma_f32 v[38:39], v[232:233], v[140:141], v[172:173]
	v_pk_fma_f32 v[40:41], v[234:235], v[142:143], v[174:175]
	v_pk_fma_f32 v[34:35], v[34:35], v[140:141], v[176:177]
	v_pk_fma_f32 v[36:37], v[36:37], v[142:143], v[178:179]
	v_cndmask_b32_dpp v232, v26, v30, vcc row_ror:8 row_mask:0xf bank_mask:0xf
	v_cndmask_b32_dpp v233, v27, v31, vcc row_ror:8 row_mask:0xf bank_mask:0xf
	v_cndmask_b32_dpp v234, v28, v32, vcc row_ror:8 row_mask:0xf bank_mask:0xf
	v_cndmask_b32_dpp v235, v29, v33, vcc row_ror:8 row_mask:0xf bank_mask:0xf
	s_not_b64 vcc, vcc
	v_cndmask_b32_dpp v26, v30, v26, vcc row_ror:8 row_mask:0xf bank_mask:0xf
	v_cndmask_b32_dpp v27, v31, v27, vcc row_ror:8 row_mask:0xf bank_mask:0xf
	v_cndmask_b32_dpp v28, v32, v28, vcc row_ror:8 row_mask:0xf bank_mask:0xf
	v_cndmask_b32_dpp v29, v33, v29, vcc row_ror:8 row_mask:0xf bank_mask:0xf
	s_not_b64 vcc, vcc
	s_waitcnt vmcnt(6)
	v_pk_fma_f32 v[30:31], v[232:233], v[132:133], v[190:191]
	v_pk_fma_f32 v[32:33], v[234:235], v[134:135], v[192:193]
	v_pk_fma_f32 v[26:27], v[26:27], v[132:133], v[194:195]
	v_pk_fma_f32 v[28:29], v[28:29], v[134:135], v[196:197]
	v_cndmask_b32_dpp v232, v18, v22, vcc row_ror:8 row_mask:0xf bank_mask:0xf
	v_cndmask_b32_dpp v233, v19, v23, vcc row_ror:8 row_mask:0xf bank_mask:0xf
	v_cndmask_b32_dpp v234, v20, v24, vcc row_ror:8 row_mask:0xf bank_mask:0xf
	v_cndmask_b32_dpp v235, v21, v25, vcc row_ror:8 row_mask:0xf bank_mask:0xf
	s_not_b64 vcc, vcc
	v_cndmask_b32_dpp v18, v22, v18, vcc row_ror:8 row_mask:0xf bank_mask:0xf
	v_cndmask_b32_dpp v19, v23, v19, vcc row_ror:8 row_mask:0xf bank_mask:0xf
	v_cndmask_b32_dpp v20, v24, v20, vcc row_ror:8 row_mask:0xf bank_mask:0xf
	v_cndmask_b32_dpp v21, v25, v21, vcc row_ror:8 row_mask:0xf bank_mask:0xf
	s_not_b64 vcc, vcc
	s_waitcnt vmcnt(4)
	v_pk_fma_f32 v[22:23], v[232:233], v[140:141], v[198:199]
	v_pk_fma_f32 v[24:25], v[234:235], v[142:143], v[200:201]
	v_pk_fma_f32 v[18:19], v[18:19], v[140:141], v[202:203]
	v_pk_fma_f32 v[20:21], v[20:21], v[142:143], v[204:205]
	v_cndmask_b32_dpp v232, v10, v14, vcc row_ror:8 row_mask:0xf bank_mask:0xf
	v_cndmask_b32_dpp v233, v11, v15, vcc row_ror:8 row_mask:0xf bank_mask:0xf
	v_cndmask_b32_dpp v234, v12, v16, vcc row_ror:8 row_mask:0xf bank_mask:0xf
	v_cndmask_b32_dpp v235, v13, v17, vcc row_ror:8 row_mask:0xf bank_mask:0xf
	s_not_b64 vcc, vcc
	v_cndmask_b32_dpp v10, v14, v10, vcc row_ror:8 row_mask:0xf bank_mask:0xf
	v_cndmask_b32_dpp v11, v15, v11, vcc row_ror:8 row_mask:0xf bank_mask:0xf
	v_cndmask_b32_dpp v12, v16, v12, vcc row_ror:8 row_mask:0xf bank_mask:0xf
	v_cndmask_b32_dpp v13, v17, v13, vcc row_ror:8 row_mask:0xf bank_mask:0xf
	s_not_b64 vcc, vcc
	s_waitcnt vmcnt(2)
	v_pk_fma_f32 v[14:15], v[232:233], v[132:133], v[206:207]
	v_pk_fma_f32 v[16:17], v[234:235], v[134:135], v[208:209]
	v_pk_fma_f32 v[10:11], v[10:11], v[132:133], v[210:211]
	v_pk_fma_f32 v[12:13], v[12:13], v[134:135], v[212:213]
	v_cndmask_b32_dpp v232, v2, v6, vcc row_ror:8 row_mask:0xf bank_mask:0xf
	v_cndmask_b32_dpp v233, v3, v7, vcc row_ror:8 row_mask:0xf bank_mask:0xf
	v_cndmask_b32_dpp v234, v4, v8, vcc row_ror:8 row_mask:0xf bank_mask:0xf
	v_cndmask_b32_dpp v235, v5, v9, vcc row_ror:8 row_mask:0xf bank_mask:0xf
	s_not_b64 vcc, vcc
	v_cndmask_b32_dpp v2, v6, v2, vcc row_ror:8 row_mask:0xf bank_mask:0xf
	v_cndmask_b32_dpp v3, v7, v3, vcc row_ror:8 row_mask:0xf bank_mask:0xf
	v_cndmask_b32_dpp v4, v8, v4, vcc row_ror:8 row_mask:0xf bank_mask:0xf
	v_cndmask_b32_dpp v5, v9, v5, vcc row_ror:8 row_mask:0xf bank_mask:0xf
	s_not_b64 vcc, vcc
	s_waitcnt vmcnt(0)
	v_pk_fma_f32 v[6:7], v[232:233], v[140:141], v[214:215]
	v_pk_fma_f32 v[8:9], v[234:235], v[142:143], v[216:217]
	v_pk_fma_f32 v[2:3], v[2:3], v[140:141], v[228:229]
	v_pk_fma_f32 v[4:5], v[4:5], v[142:143], v[230:231]
	global_store_dwordx4 v162, v[128:131], s[4:5] nt
	global_store_dwordx4 v163, v[124:127], s[4:5] nt
	global_store_dwordx4 v162, v[120:123], s[4:5] offset:512 nt
	global_store_dwordx4 v163, v[116:119], s[4:5] offset:512 nt
	s_add_u32 s4, s4, 0x10000
	s_addc_u32 s5, s5, 0
	global_store_dwordx4 v162, v[112:115], s[4:5] nt
	global_store_dwordx4 v163, v[108:111], s[4:5] nt
	global_store_dwordx4 v162, v[104:107], s[4:5] offset:512 nt
	global_store_dwordx4 v163, v[100:103], s[4:5] offset:512 nt
	s_add_u32 s4, s4, 0x10000
	s_addc_u32 s5, s5, 0
	global_store_dwordx4 v162, v[96:99], s[4:5] nt
	global_store_dwordx4 v163, v[92:95], s[4:5] nt
	global_store_dwordx4 v162, v[88:91], s[4:5] offset:512 nt
	global_store_dwordx4 v163, v[84:87], s[4:5] offset:512 nt
	s_add_u32 s4, s4, 0x10000
	s_addc_u32 s5, s5, 0
	global_store_dwordx4 v162, v[80:83], s[4:5] nt
	global_store_dwordx4 v163, v[76:79], s[4:5] nt
	global_store_dwordx4 v162, v[72:75], s[4:5] offset:512 nt
	global_store_dwordx4 v163, v[68:71], s[4:5] offset:512 nt
	s_add_u32 s4, s4, 0x50000
	s_addc_u32 s5, s5, 0
	global_store_dwordx4 v162, v[62:65], s[4:5] nt
	global_store_dwordx4 v163, v[58:61], s[4:5] nt
	global_store_dwordx4 v162, v[54:57], s[4:5] offset:512 nt
	global_store_dwordx4 v163, v[50:53], s[4:5] offset:512 nt
	s_add_u32 s4, s4, 0x10000
	s_addc_u32 s5, s5, 0
	global_store_dwordx4 v162, v[46:49], s[4:5] nt
	global_store_dwordx4 v163, v[42:45], s[4:5] nt
	global_store_dwordx4 v162, v[38:41], s[4:5] offset:512 nt
	global_store_dwordx4 v163, v[34:37], s[4:5] offset:512 nt
	s_add_u32 s4, s4, 0x10000
	s_addc_u32 s5, s5, 0
	global_store_dwordx4 v162, v[30:33], s[4:5] nt
	global_store_dwordx4 v163, v[26:29], s[4:5] nt
	global_store_dwordx4 v162, v[22:25], s[4:5] offset:512 nt
	global_store_dwordx4 v163, v[18:21], s[4:5] offset:512 nt
	s_add_u32 s4, s4, 0x10000
	s_addc_u32 s5, s5, 0
	global_store_dwordx4 v162, v[14:17], s[4:5] nt
	global_store_dwordx4 v163, v[10:13], s[4:5] nt
	global_store_dwordx4 v162, v[6:9], s[4:5] offset:512 nt
	global_store_dwordx4 v163, v[2:5], s[4:5] offset:512 nt
	s_branch .Lepi_r_done
